# v024 plus work-queue ticket prefetch: the next attention item's atomic ticket is issued one item early so its latency overlaps the current item
# speedup vs baseline: 1.0005x; 1.0005x over previous
; template <int DQK, bool ROPEQ, bool ALIBI> ...
;     ...
;     const int vb0 = (int)(size_t)Vl + v_rd_base(lane);
;     const char* pv[2]; const char* pk[NK]; unsigned stk[NK];
;     const unsigned vstride = 64u * (unsigned)ldv * 2u;
; #pragma unroll
;     for (int i = 0; i < 2; ++i) { const int s_ = i * 512 + tid, sub = s_ >> 5, w_ = s_ & 31, kk = (sub >> 2) * 8 + (w_ >> 2);
;         const int k = (kk & ~0xC) | ((kk & 4) << 1) | ((kk & 8) >> 1), c = (sub & 3) * 32 + (w_ & 3) * 8;
;         pv[i] = (const char*)(Vp + (size_t)k * ldv + c); }
;     if constexpr (DQK == 64) { const int rp_ = tid >> 3, row = (rp_ & ~9) | ((rp_ & 1) << 3) | ((rp_ >> 3) & 1), c = tid & 7, g_ = c ^ (row & 7); pk[0] = (const char*)(Ka + (size_t)row * ldka + g_ * 8); stk[0] = 64u * (unsigned)ldka * 2u; }
;     else {
; #pragma unroll
;         for (int i = 0; i < 3; ++i) { const int s_ = i * 512 + tid, rp_ = s_ / 24, row = (rp_ & ~9) | ((rp_ & 1) << 3) | ((rp_ >> 3) & 1), c = s_ % 24, g_ = (c & ~7) | ((c ^ row) & 7);
; __global__ void __launch_bounds__(512, 2) mega(Args a) {
;     ...
;         const int wid = __builtin_amdgcn_readfirstlane(tid >> 6), r32 = lane & 31, hi = lane >> 5;
;         const float lam = misc[0];
;         unsigned* qctr = barw;
;         LAS int* qslot = (LAS int*)(lds + ATT_WSOFF + 2048);
;         for (;;) {
;             if (tid == 0) *qslot = (int)atomicAdd(qctr + 0, 1u);
;             __syncthreads();
;             const int it = __builtin_amdgcn_readfirstlane(*qslot);
;             __syncthreads();
;             if (it >= 64 + 1024) break;
;             int b, h, NT, ntw, qpos, qrow0, krow0;
;             if (it < 64) { b = it >> 3; h = it & 7; NT = KS / 64; ntw = (wid < 2) ? NT : 0; qrow0 = MP + b * 64; qpos = PAST + wid * 32 + r32; krow0 = MP + b * KS; }
;             else { const int j = it - 64, qblk = 7 - (j >> 7), rem = j & 127; b = rem >> 3; h = rem & 7;
;                    NT = 4 * qblk + 4; ntw = 4 * qblk + (wid >> 1) + 1; qrow0 = b * SEQ + qblk * 256; qpos = qblk * 256 + wid * 32 + r32; krow0 = b * SEQ; }
;             const int qrow = qrow0 + wid * 32 + r32;
;             f32x16 o[4];
;             {
;                 const float slope2 = exp2f(-(float)(h + 1)) * LOG2E, C1 = 0.125f * LOG2E;
;                 attn_pass<64, false, true>(lds, qb + (size_t)qrow * 1024 + h * 128 + hi * 8, kall + (size_t)krow0 * 1024 + h * 128, 1024, nullptr,
.LBB0_1166:
	s_cmp_lt_i32 s78, 8
	s_cselect_b64 s[0:1], -1, 0
	s_and_b64 s[0:1], s[0:1], s[4:5]
	v_writelane_b32 v244, s0, 42
	s_andn2_b64 vcc, exec, s[0:1]
	v_mbcnt_lo_u32_b32 v147, -1, 0
	v_writelane_b32 v244, s1, 43
	s_cbranch_vccnz .LBB0_1250
	v_mov_b32_e32 v153, 0
	global_load_dword v130, v153, s[90:91]
	v_bfe_u32 v221, v146, 5, 1
	v_writelane_b32 v244, s88, 40
	s_movk_i32 s0, 0x60
	v_and_b32_e32 v219, 0x70, v211
	v_lshlrev_b32_e32 v220, 4, v221
	v_writelane_b32 v244, s89, 41
	s_mov_b32 s5, 0
	v_and_b32_e32 v12, 8, v146
	s_movk_i32 s1, 0x76
	v_bitop3_b32 v216, v220, v219, s0 bitop3:0x36
	s_mov_b32 s0, s86
	v_lshrrev_b32_e32 v4, 5, v146
	v_lshrrev_b32_e32 v7, 1, v146
	v_and_or_b32 v12, v205, s1, v12
	s_mov_b32 s87, s5
	v_writelane_b32 v244, s0, 44
	v_bfe_u32 v6, v146, 2, 2
	v_and_b32_e32 v8, 0x60, v146
	v_lshlrev_b32_e32 v9, 3, v146
	v_add_u32_e32 v223, 0x200, v146
	v_and_b32_e32 v7, 8, v7
	v_and_b32_e32 v16, 4, v4
	v_writelane_b32 v244, s1, 45
	s_lshl_b64 s[0:1], s[86:87], 17
	s_movk_i32 s2, 0x70
	v_readfirstlane_b32 s3, v146
	v_and_or_b32 v4, v9, 24, v8
	v_lshrrev_b32_e32 v8, 4, v223
	v_or3_b32 v6, v16, v6, v7
	s_add_u32 s0, s25, s0
	v_lshlrev_b32_e32 v152, 8, v146
	v_bitop3_b32 v155, v220, v211, s2 bitop3:0x78
	v_and_or_b32 v226, v8, s2, v6
	s_addc_u32 s1, s24, s1
	s_lshr_b32 s2, s3, 7
	s_lshr_b32 s4, s3, 1
	v_lshl_add_u64 v[134:135], s[0:1], 0, v[152:153]
	s_add_i32 s0, s2, 1
	v_writelane_b32 v244, s0, 46
	s_and_b32 s0, s4, 0x7fffffe0
	s_cmpk_lt_u32 s3, 0x80
	v_readlane_b32 s8, v244, 8
	s_cselect_b32 s1, 0x41, 0
	v_and_b32_e32 v151, 31, v146
	v_bfe_u32 v13, v146, 6, 1
	v_readlane_b32 s9, v244, 9
	v_readlane_b32 s10, v244, 10
	v_readlane_b32 s11, v244, 11
	v_readlane_b32 s12, v244, 12
	v_readlane_b32 s13, v244, 13
	v_readlane_b32 s14, v244, 14
	v_readlane_b32 s15, v244, 15
	v_readlane_b32 s16, v244, 16
	v_readlane_b32 s17, v244, 17
	v_readlane_b32 s18, v244, 18
	v_readlane_b32 s19, v244, 19
	v_readlane_b32 s20, v244, 20
	v_readlane_b32 s21, v244, 21
	v_readlane_b32 s22, v244, 22
	v_readlane_b32 s23, v244, 23
	v_writelane_b32 v244, s1, 47
	v_lshrrev_b32_e32 v10, 4, v146
	v_or_b32_e32 v7, v12, v13
	v_bitop3_b32 v12, v12, v146, v13 bitop3:0x36
	v_or_b32_e32 v218, s0, v151
	v_writelane_b32 v244, s0, 48
	s_addk_i32 s0, 0x1000
	s_waitcnt lgkmcnt(0)
	v_lshrrev_b32_e32 v3, 5, v148
	v_lshlrev_b32_e32 v5, 1, v146
	v_and_b32_e32 v14, 22, v146
	v_bfe_u32 v15, v146, 3, 1
	v_and_b32_e32 v17, 0x118, v9
	v_and_b32_e32 v9, 8, v9
	v_and_or_b32 v225, v10, 48, v6
	v_lshlrev_b32_e32 v6, 10, v7
	v_lshlrev_b32_e32 v7, 3, v12
	v_writelane_b32 v244, s0, 49
	s_add_i32 s0, 0, 0x1e800
	v_and_b32_e32 v11, 0xc0, v211
	v_lshlrev_b32_e32 v2, 3, v3
	v_lshlrev_b32_e32 v18, 2, v221
	v_and_or_b32 v5, v5, 32, v17
	v_or3_b32 v222, v14, v9, v15
	v_lshlrev_b32_e32 v8, 10, v225
	v_lshlrev_b32_e32 v10, 10, v226
	v_and_b32_e32 v12, 56, v7
	v_lshlrev_b32_e32 v152, 4, v3
	v_writelane_b32 v244, s0, 50
	s_mov_b32 s16, -2.0
	s_mov_b32 s18, 0xc1000000
	s_mov_b32 s22, 0xc1200000
	s_mov_b32 s40, 0xc1800000
	s_mov_b32 s42, 0xc1900000
	s_mov_b32 s44, 0xc1c00000
	s_mov_b32 s46, 0xc1d00000
	s_mov_b32 s48, 0xc2680000
	s_mov_b32 s50, 0xc2600000
	s_mov_b32 s52, 0xc2480000
	s_mov_b32 s54, 0xc2400000
	s_mov_b32 s56, 0xc2280000
	s_mov_b32 s58, 0xc2200000
	s_mov_b32 s60, 0xc2080000
	s_mov_b32 s62, 0xc2000000
	s_mov_b32 s64, 2.0
	s_mov_b32 s66, 0x41000000
	s_mov_b32 s68, 0x41200000
	s_mov_b32 s90, 0x41800000
	s_mov_b32 s92, 0x41900000
	s_mov_b32 s94, 0x41c00000
	s_mov_b32 s96, 0x41d00000
	s_mov_b32 s34, 0x42680000
	s_mov_b32 s28, 0x42600000
	s_mov_b32 s80, 0x42480000
	s_mov_b32 s82, 0x42400000
	s_mov_b32 s10, 0x42280000
	s_mov_b32 s88, 0x42200000
	s_mov_b32 s12, 0x42080000
	s_mov_b32 s86, 0x42000000
	s_mov_b64 s[6:7], 0x20000
	v_lshlrev_b32_e32 v154, 2, v3
	v_bitop3_b32 v214, v220, v219, 32 bitop3:0x36
	v_bitop3_b32 v215, v220, v219, 64 bitop3:0x36
	v_sub_u32_e32 v227, v151, v18
	v_lshl_add_u32 v224, v222, 7, 0
	v_add3_u32 v217, v11, 0, v5
	v_lshlrev_b32_e32 v132, 1, v6
	v_lshlrev_b32_e32 v136, 1, v8
	v_lshlrev_b32_e32 v138, 1, v10
	v_lshlrev_b32_e32 v140, 1, v12
	v_lshl_add_u64 v[142:143], s[8:9], 0, v[152:153]
	v_mov_b32_e32 v228, s0
	s_waitcnt vmcnt(0)
	v_mov_b32_e32 v131, v130
	s_mov_b32 s17, 0xc0400000
	s_mov_b32 s19, 0xc1100000
	s_mov_b32 s23, 0xc1300000
	s_mov_b32 s41, 0xc1880000
	s_mov_b32 s43, 0xc1980000
	s_mov_b32 s45, 0xc1c80000
	s_mov_b32 s47, 0xc1d80000
	s_mov_b32 s49, 0xc26c0000
	s_mov_b32 s51, 0xc2640000
	s_mov_b32 s53, 0xc24c0000
	s_mov_b32 s55, 0xc2440000
	s_mov_b32 s57, 0xc22c0000
	s_mov_b32 s59, 0xc2240000
	s_mov_b32 s61, 0xc20c0000
	s_mov_b32 s63, 0xc2040000
	s_mov_b32 s65, 0x40400000
	s_mov_b32 s67, 0x41100000
	s_mov_b32 s69, 0x41300000
	s_mov_b32 s91, 0x41880000
	s_mov_b32 s93, 0x41980000
	s_mov_b32 s95, 0x41c80000
	s_mov_b32 s97, 0x41d80000
	s_mov_b32 s35, 0x426c0000
	s_mov_b32 s29, 0x42640000
	s_mov_b32 s81, 0x424c0000
	s_mov_b32 s83, 0x42440000
	s_mov_b32 s11, 0x422c0000
	s_mov_b32 s89, 0x42240000
	s_mov_b32 s13, 0x420c0000
	s_mov_b32 s87, 0x42040000
	s_mov_b32 s33, 0x4138aa3b
	v_mov_b32_e32 v229, 0x358637bd
	v_lshlrev_b32_e32 v152, 1, v4
	v_lshlrev_b32_e32 v156, 1, v2
	v_mov_b32_e32 v230, 0x42800000
	v_mbcnt_hi_u32_b32 v231, -1, v147
	v_writelane_b32 v244, s84, 51
	s_nop 1
	v_writelane_b32 v244, s85, 52
	s_mov_b64 s[20:21], exec
	v_readlane_b32 s0, v244, 6
	v_readlane_b32 s1, v244, 7
	s_and_b64 s[0:1], s[20:21], s[0:1]
	s_mov_b64 exec, s[0:1]
	s_cbranch_execz .Lqp1_skip
	v_mov_b32_e32 v255, 1
	v_readlane_b32 s0, v244, 3
	v_readlane_b32 s1, v244, 4
	s_nop 4
	global_atomic_add v255, v153, v255, s[0:1] sc0
.Lqp1_skip:
	s_mov_b64 exec, s[20:21]
	s_branch .LBB0_1170

; __global__ void __launch_bounds__(512, 2) mega(Args a) {
;     ...
;         for (;;) {
;             if (tid == 0) *qslot = (int)atomicAdd(qctr + 0, 1u);
;             __syncthreads();
;             const int it = __builtin_amdgcn_readfirstlane(*qslot);
;             __syncthreads();
;             if (it >= 64 + 1024) break;
.LBB0_1170:
	s_mov_b64 s[20:21], exec
	v_readlane_b32 s0, v244, 6
	v_readlane_b32 s1, v244, 7
	s_and_b64 s[0:1], s[20:21], s[0:1]
	s_mov_b64 exec, s[0:1]
	s_cbranch_execz .LBB0_1174
	s_mov_b64 s[30:31], exec
	v_mbcnt_lo_u32_b32 v2, s30, 0
	v_mbcnt_hi_u32_b32 v2, s31, v2
	v_cmp_eq_u32_e32 vcc, 0, v2
	s_and_saveexec_b64 s[24:25], vcc
	s_cbranch_execz .LBB0_1173
	s_waitcnt vmcnt(0)
	v_mov_b32_e32 v3, v255
	s_bcnt1_i32_b64 s0, s[30:31]
	v_mov_b32_e32 v255, s0
	v_readlane_b32 s0, v244, 3
	v_readlane_b32 s1, v244, 4
	s_nop 4
	global_atomic_add v255, v153, v255, s[0:1] sc0
.LBB0_1173:
	s_or_b64 exec, exec, s[24:25]
	v_readfirstlane_b32 s0, v3
	s_nop 1
	v_add_u32_e32 v2, s0, v2
	v_readlane_b32 s0, v244, 50
	s_nop 1
	v_mov_b32_e32 v3, s0
	ds_write_b32 v3, v2

; template <int DQK, bool ROPEQ, bool ALIBI> ...
;     ...
;     for (int i = 0; i < 2; ++i) { const int s_ = i * 512 + tid, sub = s_ >> 5, w_ = s_ & 31, kk = (sub >> 2) * 8 + (w_ >> 2);
;         const int k = (kk & ~0xC) | ((kk & 4) << 1) | ((kk & 8) >> 1), c = (sub & 3) * 32 + (w_ & 3) * 8;
;         pv[i] = (const char*)(Vp + (size_t)k * ldv + c); }
;     if constexpr (DQK == 64) { const int rp_ = tid >> 3, row = (rp_ & ~9) | ((rp_ & 1) << 3) | ((rp_ >> 3) & 1), c = tid & 7, g_ = c ^ (row & 7); pk[0] = (const char*)(Ka + (size_t)row * ldka + g_ * 8); stk[0] = 64u * (unsigned)ldka * 2u; }
;     else {
; #pragma unroll
;         for (int i = 0; i < 3; ++i) { const int s_ = i * 512 + tid, rp_ = s_ / 24, row = (rp_ & ~9) | ((rp_ & 1) << 3) | ((rp_ >> 3) & 1), c = s_ % 24, g_ = (c & ~7) | ((c ^ row) & 7);
;             if (g_ < 16) { pk[i] = (const char*)(Ka + (size_t)row * ldka + g_ * 8); stk[i] = 64u * (unsigned)ldka * 2u; }
;             else { pk[i] = (const char*)(Kb + (size_t)row * 64 + (g_ - 16) * 8); stk[i] = 64u * 64u * 2u; } }
;     }
; __global__ void __launch_bounds__(512, 2) mega(Args a) {
;     ...
;         for (;;) {
;             if (tid == 0) *qslot = (int)atomicAdd(qctr + 1, 1u);
;             __syncthreads();
;             const int it = __builtin_amdgcn_readfirstlane(*qslot);
;             __syncthreads();
;             if (it >= 64 + 1024) break;
;             int b, h, NT, ntw, qpos, qrow0, krow0;
;             if (it < 64) { b = it >> 3; h = it & 7; NT = KS / 64; ntw = (wid < 2) ? NT : 0; qrow0 = MP + b * 64; qpos = PAST + wid * 32 + r32; krow0 = MP + b * KS; }
;             else { const int j = it - 64, qblk = 7 - (j >> 7), rem = j & 127; b = rem >> 3; h = rem & 7;
;                    NT = 4 * qblk + 4; ntw = 4 * qblk + (wid >> 1) + 1; qrow0 = b * SEQ + qblk * 256; qpos = qblk * 256 + wid * 32 + r32; krow0 = b * SEQ; }
;             const int qrow = qrow0 + wid * 32 + r32;
;             f32x16 o[4];
;             {
;                 const float C1 = 0.07216878364870322f * LOG2E;
;                 attn_pass<192, true, false>(lds, qm + (size_t)qrow * 1536 + h * 192 + hi * 8, kvm + (size_t)krow0 * 2048 + h * 256, 2048, kra + (size_t)krow0 * 64,
;                                             kvm + (size_t)krow0 * 2048 + h * 256 + 128, 2048, NT, ntw, qpos, C1, 0.f, ropetab, o);
.LBB0_1221:
	v_mul_u32_u24_e32 v3, 0xaab, v146
	v_mov_b32_e32 v5, 54
	v_and_b32_sdwa v5, v3, v5 dst_sel:DWORD dst_unused:UNUSED_PAD src0_sel:WORD_1 src1_sel:DWORD
	v_lshrrev_b32_e32 v6, 13, v3
	v_mov_b32_e32 v9, 24
	v_and_or_b32 v5, v6, 8, v5
	v_bfe_u32 v6, v3, 19, 1
	v_mul_lo_u16_sdwa v3, v3, v9 dst_sel:DWORD dst_unused:UNUSED_PAD src0_sel:WORD_1 src1_sel:DWORD
	v_sub_u16_e32 v3, v146, v3
	v_or_b32_e32 v7, v5, v6
	v_and_b32_e32 v8, 24, v3
	v_bitop3_b32 v5, v5, v3, v6 bitop3:0x36
	v_and_or_b32 v5, v5, 7, v8
	v_lshlrev_b32_e32 v6, 3, v5
	v_mul_u32_u24_e32 v5, 0xaab, v223
	s_movk_i32 s1, 0x76
	v_lshlrev_b32_e32 v8, 6, v7
	v_lshlrev_b32_e32 v10, 11, v7
	v_and_b32_sdwa v7, v5, s1 dst_sel:DWORD dst_unused:UNUSED_PAD src0_sel:WORD_1 src1_sel:DWORD
	v_lshrrev_b32_e32 v11, 13, v5
	v_and_or_b32 v7, v11, 8, v7
	v_bfe_u32 v11, v5, 19, 1
	v_mul_lo_u16_sdwa v5, v5, v9 dst_sel:DWORD dst_unused:UNUSED_PAD src0_sel:WORD_1 src1_sel:DWORD
	v_sub_u16_e32 v5, v223, v5
	v_or_b32_e32 v13, v7, v11
	v_and_b32_e32 v12, 24, v5
	v_bitop3_b32 v7, v7, v5, v11 bitop3:0x36
	v_and_or_b32 v7, v7, 7, v12
	s_movk_i32 s0, 0xaab
	v_lshlrev_b32_e32 v12, 3, v7
	v_or_b32_e32 v7, 0x400, v146
	v_mul_u32_u24_sdwa v11, v7, s0 dst_sel:DWORD dst_unused:UNUSED_PAD src0_sel:WORD_0 src1_sel:DWORD
	v_lshlrev_b32_e32 v14, 6, v13
	v_lshlrev_b32_e32 v16, 11, v13
	v_and_b32_sdwa v13, v11, s1 dst_sel:DWORD dst_unused:UNUSED_PAD src0_sel:WORD_1 src1_sel:DWORD
	v_mov_b32_e32 v153, 0
	v_readlane_b32 s0, v244, 26
	v_lshlrev_b32_e32 v24, 6, v221
	v_mov_b32_e32 v25, v153
	v_readlane_b32 s1, v244, 27
	v_lshrrev_b32_e32 v15, 13, v11
	v_mul_lo_u16_sdwa v9, v11, v9 dst_sel:DWORD dst_unused:UNUSED_PAD src0_sel:WORD_1 src1_sel:DWORD
	v_lshl_add_u64 v[158:159], s[0:1], 0, v[24:25]
	s_movk_i32 s0, 0x160
	v_bitop3_b32 v201, v220, v219, s0 bitop3:0x36
	s_movk_i32 s0, 0x80
	v_bitop3_b32 v202, v220, v219, s0 bitop3:0x36
	s_movk_i32 s0, 0xa0
	v_bitop3_b32 v203, v220, v219, s0 bitop3:0x36
	s_movk_i32 s0, 0xc0
	v_bitop3_b32 v204, v220, v219, s0 bitop3:0x36
	s_movk_i32 s0, 0xe0
	v_and_or_b32 v13, v15, 8, v13
	v_bfe_u32 v15, v11, 19, 1
	v_sub_u16_e32 v7, v7, v9
	v_bitop3_b32 v206, v220, v219, s0 bitop3:0x36
	s_movk_i32 s0, 0x100
	v_and_b32_e32 v9, 24, v7
	v_bitop3_b32 v11, v13, v7, v15 bitop3:0x36
	v_bitop3_b32 v207, v220, v219, s0 bitop3:0x36
	s_movk_i32 s0, 0x120
	v_or_b32_e32 v17, v13, v15
	v_and_or_b32 v9, v11, 7, v9
	s_add_u32 s10, s76, 0x3d8f5004
	v_bitop3_b32 v221, v220, v219, s0 bitop3:0x36
	s_movk_i32 s0, 0x140
	v_lshlrev_b32_e32 v2, 11, v225
	v_lshlrev_b32_e32 v4, 11, v226
	v_lshlrev_b32_e32 v18, 3, v9
	v_lshlrev_b32_e32 v20, 6, v17
	v_lshlrev_b32_e32 v22, 11, v17
	s_addc_u32 s11, s77, 0
	v_bitop3_b32 v219, v220, v219, s0 bitop3:0x36
	v_mov_b32_e32 v9, 0x2000
	v_mov_b32_e32 v11, 0x40000
	v_cmp_gt_u16_e64 s[4:5], 16, v3
	v_cmp_gt_u16_e64 s[6:7], 16, v5
	v_cmp_gt_u16_e64 s[8:9], 16, v7
	s_add_i32 s0, 0, 0x1e800
	s_movk_i32 s18, 0xff00
	v_readlane_b32 s88, v244, 40
	v_lshl_add_u32 v200, v222, 8, v224
	v_cndmask_b32_e64 v160, v9, v11, s[4:5]
	v_mov_b32_e32 v161, v153
	v_cndmask_b32_e64 v162, v9, v11, s[6:7]
	v_mov_b32_e32 v163, v153
	v_cndmask_b32_e64 v164, v9, v11, s[8:9]
	v_mov_b32_e32 v165, v153
	s_mov_b32 s13, 0
	v_lshlrev_b32_e32 v166, 1, v2
	s_mov_b64 s[16:17], 0x100
	v_lshlrev_b32_e32 v168, 1, v4
	v_lshlrev_b32_e32 v170, 1, v10
	v_lshlrev_b32_e32 v172, 1, v6
	v_lshlrev_b32_e32 v174, 1, v8
	s_mov_b32 s19, -1
	v_lshlrev_b32_e32 v176, 1, v16
	v_lshlrev_b32_e32 v178, 1, v12
	v_lshlrev_b32_e32 v180, 1, v14
	v_lshlrev_b32_e32 v182, 1, v22
	v_lshlrev_b32_e32 v184, 1, v18
	v_lshlrev_b32_e32 v186, 1, v20
	s_mov_b64 s[20:21], 0x40100
	s_add_i32 s1, 0, 0xc000
	s_movk_i32 s3, 0xc00
	s_mov_b64 s[22:23], 0x80000
	s_mov_b64 s[26:27], 0x40000
	s_mov_b32 s33, 0x4138aa3b
	v_mov_b32_e32 v220, s0
	v_readlane_b32 s86, v244, 44
	v_readlane_b32 s89, v244, 41
	v_readlane_b32 s87, v244, 45
	s_mov_b64 s[28:29], exec
	v_readlane_b32 s14, v244, 6
	v_readlane_b32 s15, v244, 7
	s_and_b64 s[14:15], s[28:29], s[14:15]
	s_mov_b64 exec, s[14:15]
	s_cbranch_execz .Lqp2_skip
	s_waitcnt vmcnt(0)
	v_mov_b32_e32 v255, 1
	global_atomic_add v255, v153, v255, s[10:11] sc0
.Lqp2_skip:
	s_mov_b64 exec, s[28:29]
	s_branch .LBB0_1224

; __global__ void __launch_bounds__(512, 2) mega(Args a) {
;     ...
;             if (tid == 0) *qslot = (int)atomicAdd(qctr + 1, 1u);
;             __syncthreads();
;             const int it = __builtin_amdgcn_readfirstlane(*qslot);
;             __syncthreads();
;             if (it >= 64 + 1024) break;
.LBB0_1224:
	s_mov_b64 s[28:29], exec
	v_readlane_b32 s14, v244, 6
	v_readlane_b32 s15, v244, 7
	s_and_b64 s[14:15], s[28:29], s[14:15]
	s_mov_b64 exec, s[14:15]
	s_cbranch_execz .LBB0_1228
	s_mov_b64 s[30:31], exec
	v_mbcnt_lo_u32_b32 v2, s30, 0
	v_mbcnt_hi_u32_b32 v2, s31, v2
	v_cmp_eq_u32_e32 vcc, 0, v2
	s_and_saveexec_b64 s[24:25], vcc
	s_cbranch_execz .LBB0_1227
	s_waitcnt vmcnt(0)
	v_mov_b32_e32 v3, v255
	s_bcnt1_i32_b64 s2, s[30:31]
	v_mov_b32_e32 v255, s2
	global_atomic_add v255, v153, v255, s[10:11] sc0
.LBB0_1227:
	s_or_b64 exec, exec, s[24:25]
	v_readfirstlane_b32 s2, v3
	v_mov_b32_e32 v3, s0
	s_nop 0
	v_add_u32_e32 v2, s2, v2
	ds_write_b32 v3, v2
